# prep1 xg: 24 rows per half-workgroup in one latency round on the 342 non-bias half-workgroups (bias half-workgroups get no xg rows); grid 256 only, old block as fallback
# speedup vs baseline: 1.0098x; 1.0022x over previous
.LBB0_92:
	s_cmpk_lg_i32 s70, 0x200
	s_cbranch_scc1 .Lxg_old
	s_sub_i32 s52, s33, 0x58
	s_cmpk_lt_i32 s33, 0x200
	s_cbranch_scc1 .Lxg6_w
	s_sub_i32 s52, s33, 0x258
.Lxg6_w:
	s_cmp_lt_i32 s52, 0
	s_cbranch_scc1 .Lxg6_end
	s_cmpk_gt_i32 s52, 0x155
	s_cbranch_scc1 .Lxg6_end
	v_lshrrev_b32_e32 v0, 6, v229
	s_nop 0
	v_readfirstlane_b32 s53, v0
	s_nop 3
	s_lshl_b32 s52, s52, 2
	s_add_i32 s52, s52, s53
	s_cmpk_gt_i32 s52, 0x556
	s_cbranch_scc1 .Lxg6_end
	v_readlane_b32 s40, v254, 5
	v_readlane_b32 s41, v254, 6
	v_readlane_b32 s42, v254, 7
	v_readlane_b32 s43, v254, 8
	v_readlane_b32 s54, v255, 7
	v_readlane_b32 s55, v255, 8
	s_nop 3
	s_cmpk_lt_i32 s52, 0x2ab
	s_cbranch_scc0 .Lxg6_smp
	s_mul_i32 s44, s52, 6
	s_movk_i32 s45, 0xfff
	s_mov_b32 s46, 0
	s_mov_b32 s47, 0
	s_mov_b64 s[48:49], s[40:41]
	s_branch .Lxg6_seg
.Lxg6_smp:
	s_sub_i32 s52, s52, 0x2ab
	s_mov_b32 s47, 0
	s_cmpk_lt_i32 s52, 0xab
	s_cbranch_scc1 .Lxg6_sg
	s_sub_i32 s52, s52, 0xab
	s_add_i32 s47, s47, 1
	s_cmpk_lt_i32 s52, 0xab
	s_cbranch_scc1 .Lxg6_sg
	s_sub_i32 s52, s52, 0xab
	s_add_i32 s47, s47, 1
	s_cmpk_lt_i32 s52, 0xab
	s_cbranch_scc1 .Lxg6_sg
	s_sub_i32 s52, s52, 0xab
	s_add_i32 s47, s47, 1
.Lxg6_sg:
	s_lshl_b32 s45, s47, 10
	s_add_i32 s45, s45, 0x1000
	s_mul_i32 s44, s52, 6
	s_add_i32 s44, s44, s45
	s_add_i32 s45, s45, 0x3ff
	s_movk_i32 s46, 0x1000
	s_add_i32 s47, s47, 1
	s_mov_b64 s[48:49], s[42:43]
.Lxg6_seg:
	s_mul_i32 s53, s47, 0x6000
	s_add_u32 s50, s54, s53
	s_addc_u32 s51, s55, 0
	s_add_u32 s50, s50, 0x1000
	s_addc_u32 s51, s51, 0
	v_lshrrev_b32_e32 v18, 1, v200
	v_lshrrev_b32_e32 v19, 2, v200
	s_add_i32 s2, s44, 0
	s_min_i32 s2, s2, s45
	s_sub_i32 s3, s2, s46
	s_lshl_b32 s3, s3, 12
	v_add_u32_e32 v48, s3, v200
	s_lshl_b32 s3, s2, 11
	v_add_u32_e32 v54, s3, v18
	s_lshl_b32 s3, s2, 7
	v_add_u32_e32 v60, s3, v19
	s_add_i32 s2, s44, 1
	s_min_i32 s2, s2, s45
	s_sub_i32 s3, s2, s46
	s_lshl_b32 s3, s3, 12
	v_add_u32_e32 v49, s3, v200
	s_lshl_b32 s3, s2, 11
	v_add_u32_e32 v55, s3, v18
	s_lshl_b32 s3, s2, 7
	v_add_u32_e32 v61, s3, v19
	s_add_i32 s2, s44, 2
	s_min_i32 s2, s2, s45
	s_sub_i32 s3, s2, s46
	s_lshl_b32 s3, s3, 12
	v_add_u32_e32 v50, s3, v200
	s_lshl_b32 s3, s2, 11
	v_add_u32_e32 v56, s3, v18
	s_lshl_b32 s3, s2, 7
	v_add_u32_e32 v62, s3, v19
	s_add_i32 s2, s44, 3
	s_min_i32 s2, s2, s45
	s_sub_i32 s3, s2, s46
	s_lshl_b32 s3, s3, 12
	v_add_u32_e32 v51, s3, v200
	s_lshl_b32 s3, s2, 11
	v_add_u32_e32 v57, s3, v18
	s_lshl_b32 s3, s2, 7
	v_add_u32_e32 v63, s3, v19
	s_add_i32 s2, s44, 4
	s_min_i32 s2, s2, s45
	s_sub_i32 s3, s2, s46
	s_lshl_b32 s3, s3, 12
	v_add_u32_e32 v52, s3, v200
	s_lshl_b32 s3, s2, 11
	v_add_u32_e32 v58, s3, v18
	s_lshl_b32 s3, s2, 7
	v_add_u32_e32 v16, s3, v19
	s_add_i32 s2, s44, 5
	s_min_i32 s2, s2, s45
	s_sub_i32 s3, s2, s46
	s_lshl_b32 s3, s3, 12
	v_add_u32_e32 v53, s3, v200
	s_lshl_b32 s3, s2, 11
	v_add_u32_e32 v59, s3, v18
	s_lshl_b32 s3, s2, 7
	v_add_u32_e32 v17, s3, v19
	global_load_dwordx4 v[20:23], v[128:129], off
	global_load_dwordx4 v[24:27], v[128:129], off offset:1024
	global_load_dwordx4 v[28:31], v[128:129], off offset:2048
	global_load_dwordx4 v[32:35], v[128:129], off offset:3072
	global_load_dwordx4 v[146:149], v200, s[50:51]
	global_load_dwordx4 v[150:153], v200, s[50:51] offset:1024
	global_load_dwordx4 v[154:157], v200, s[50:51] offset:2048
	global_load_dwordx4 v[158:161], v200, s[50:51] offset:3072
	global_load_dwordx4 v[64:67], v48, s[48:49]
	global_load_dwordx4 v[68:71], v48, s[48:49] offset:1024
	global_load_dwordx4 v[72:75], v48, s[48:49] offset:2048
	global_load_dwordx4 v[76:79], v48, s[48:49] offset:3072
	global_load_dwordx4 v[80:83], v49, s[48:49]
	global_load_dwordx4 v[84:87], v49, s[48:49] offset:1024
	global_load_dwordx4 v[88:91], v49, s[48:49] offset:2048
	global_load_dwordx4 v[92:95], v49, s[48:49] offset:3072
	global_load_dwordx4 v[96:99], v50, s[48:49]
	global_load_dwordx4 v[100:103], v50, s[48:49] offset:1024
	global_load_dwordx4 v[104:107], v50, s[48:49] offset:2048
	global_load_dwordx4 v[108:111], v50, s[48:49] offset:3072
	global_load_dwordx4 v[112:115], v51, s[48:49]
	global_load_dwordx4 v[116:119], v51, s[48:49] offset:1024
	global_load_dwordx4 v[120:123], v51, s[48:49] offset:2048
	global_load_dwordx4 v[124:127], v51, s[48:49] offset:3072
	global_load_dwordx4 v[162:165], v52, s[48:49]
	global_load_dwordx4 v[166:169], v52, s[48:49] offset:1024
	global_load_dwordx4 v[170:173], v52, s[48:49] offset:2048
	global_load_dwordx4 v[174:177], v52, s[48:49] offset:3072
	global_load_dwordx4 v[178:181], v53, s[48:49]
	global_load_dwordx4 v[182:185], v53, s[48:49] offset:1024
	global_load_dwordx4 v[186:189], v53, s[48:49] offset:2048
	global_load_dwordx4 v[190:193], v53, s[48:49] offset:3072
	s_waitcnt vmcnt(24)
	v_pk_add_f32 v[146:147], v[146:147], 1.0 op_sel_hi:[1,0]
	v_pk_add_f32 v[148:149], v[148:149], 1.0 op_sel_hi:[1,0]
	v_pk_add_f32 v[150:151], v[150:151], 1.0 op_sel_hi:[1,0]
	v_pk_add_f32 v[152:153], v[152:153], 1.0 op_sel_hi:[1,0]
	v_pk_add_f32 v[154:155], v[154:155], 1.0 op_sel_hi:[1,0]
	v_pk_add_f32 v[156:157], v[156:157], 1.0 op_sel_hi:[1,0]
	v_pk_add_f32 v[158:159], v[158:159], 1.0 op_sel_hi:[1,0]
	v_pk_add_f32 v[160:161], v[160:161], 1.0 op_sel_hi:[1,0]
	s_waitcnt vmcnt(20)
	v_mul_f32_e32 v12, v65, v65
	v_fmac_f32_e32 v12, v64, v64
	v_fmac_f32_e32 v12, v66, v66
	v_fmac_f32_e32 v12, v67, v67
	v_mul_f32_e32 v13, v69, v69
	v_fmac_f32_e32 v13, v68, v68
	v_fmac_f32_e32 v13, v70, v70
	v_fmac_f32_e32 v13, v71, v71
	v_mul_f32_e32 v14, v73, v73
	v_fmac_f32_e32 v14, v72, v72
	v_fmac_f32_e32 v14, v74, v74
	v_fmac_f32_e32 v14, v75, v75
	v_mul_f32_e32 v15, v77, v77
	v_fmac_f32_e32 v15, v76, v76
	v_fmac_f32_e32 v15, v78, v78
	v_fmac_f32_e32 v15, v79, v79
	v_add_f32_e32 v36, v12, v13
	v_add_f32_e32 v36, v36, v14
	v_add_f32_e32 v36, v36, v15
	v_pk_mul_f32 v[64:65], v[64:65], v[20:21]
	v_pk_mul_f32 v[66:67], v[66:67], v[22:23]
	v_pk_mul_f32 v[64:65], v[64:65], v[146:147]
	v_pk_mul_f32 v[66:67], v[66:67], v[148:149]
	v_cvt_pk_bf16_f32 v64, v64, v65
	v_cvt_pk_bf16_f32 v65, v66, v67
	v_pk_mul_f32 v[68:69], v[68:69], v[24:25]
	v_pk_mul_f32 v[70:71], v[70:71], v[26:27]
	v_pk_mul_f32 v[68:69], v[68:69], v[150:151]
	v_pk_mul_f32 v[70:71], v[70:71], v[152:153]
	v_cvt_pk_bf16_f32 v68, v68, v69
	v_cvt_pk_bf16_f32 v69, v70, v71
	v_pk_mul_f32 v[72:73], v[72:73], v[28:29]
	v_pk_mul_f32 v[74:75], v[74:75], v[30:31]
	v_pk_mul_f32 v[72:73], v[72:73], v[154:155]
	v_pk_mul_f32 v[74:75], v[74:75], v[156:157]
	v_cvt_pk_bf16_f32 v72, v72, v73
	v_cvt_pk_bf16_f32 v73, v74, v75
	v_pk_mul_f32 v[76:77], v[76:77], v[32:33]
	v_pk_mul_f32 v[78:79], v[78:79], v[34:35]
	v_pk_mul_f32 v[76:77], v[76:77], v[158:159]
	v_pk_mul_f32 v[78:79], v[78:79], v[160:161]
	v_cvt_pk_bf16_f32 v76, v76, v77
	v_cvt_pk_bf16_f32 v77, v78, v79
	global_store_dwordx2 v54, v[64:65], s[14:15]
	global_store_dwordx2 v54, v[68:69], s[14:15] offset:512
	global_store_dwordx2 v54, v[72:73], s[14:15] offset:1024
	global_store_dwordx2 v54, v[76:77], s[14:15] offset:1536
	s_waitcnt vmcnt(20)
	v_mul_f32_e32 v12, v81, v81
	v_fmac_f32_e32 v12, v80, v80
	v_fmac_f32_e32 v12, v82, v82
	v_fmac_f32_e32 v12, v83, v83
	v_mul_f32_e32 v13, v85, v85
	v_fmac_f32_e32 v13, v84, v84
	v_fmac_f32_e32 v13, v86, v86
	v_fmac_f32_e32 v13, v87, v87
	v_mul_f32_e32 v14, v89, v89
	v_fmac_f32_e32 v14, v88, v88
	v_fmac_f32_e32 v14, v90, v90
	v_fmac_f32_e32 v14, v91, v91
	v_mul_f32_e32 v15, v93, v93
	v_fmac_f32_e32 v15, v92, v92
	v_fmac_f32_e32 v15, v94, v94
	v_fmac_f32_e32 v15, v95, v95
	v_add_f32_e32 v37, v12, v13
	v_add_f32_e32 v37, v37, v14
	v_add_f32_e32 v37, v37, v15
	v_pk_mul_f32 v[80:81], v[80:81], v[20:21]
	v_pk_mul_f32 v[82:83], v[82:83], v[22:23]
	v_pk_mul_f32 v[80:81], v[80:81], v[146:147]
	v_pk_mul_f32 v[82:83], v[82:83], v[148:149]
	v_cvt_pk_bf16_f32 v80, v80, v81
	v_cvt_pk_bf16_f32 v81, v82, v83
	v_pk_mul_f32 v[84:85], v[84:85], v[24:25]
	v_pk_mul_f32 v[86:87], v[86:87], v[26:27]
	v_pk_mul_f32 v[84:85], v[84:85], v[150:151]
	v_pk_mul_f32 v[86:87], v[86:87], v[152:153]
	v_cvt_pk_bf16_f32 v84, v84, v85
	v_cvt_pk_bf16_f32 v85, v86, v87
	v_pk_mul_f32 v[88:89], v[88:89], v[28:29]
	v_pk_mul_f32 v[90:91], v[90:91], v[30:31]
	v_pk_mul_f32 v[88:89], v[88:89], v[154:155]
	v_pk_mul_f32 v[90:91], v[90:91], v[156:157]
	v_cvt_pk_bf16_f32 v88, v88, v89
	v_cvt_pk_bf16_f32 v89, v90, v91
	v_pk_mul_f32 v[92:93], v[92:93], v[32:33]
	v_pk_mul_f32 v[94:95], v[94:95], v[34:35]
	v_pk_mul_f32 v[92:93], v[92:93], v[158:159]
	v_pk_mul_f32 v[94:95], v[94:95], v[160:161]
	v_cvt_pk_bf16_f32 v92, v92, v93
	v_cvt_pk_bf16_f32 v93, v94, v95
	global_store_dwordx2 v55, v[80:81], s[14:15]
	global_store_dwordx2 v55, v[84:85], s[14:15] offset:512
	global_store_dwordx2 v55, v[88:89], s[14:15] offset:1024
	global_store_dwordx2 v55, v[92:93], s[14:15] offset:1536
	s_waitcnt vmcnt(20)
	v_mul_f32_e32 v12, v97, v97
	v_fmac_f32_e32 v12, v96, v96
	v_fmac_f32_e32 v12, v98, v98
	v_fmac_f32_e32 v12, v99, v99
	v_mul_f32_e32 v13, v101, v101
	v_fmac_f32_e32 v13, v100, v100
	v_fmac_f32_e32 v13, v102, v102
	v_fmac_f32_e32 v13, v103, v103
	v_mul_f32_e32 v14, v105, v105
	v_fmac_f32_e32 v14, v104, v104
	v_fmac_f32_e32 v14, v106, v106
	v_fmac_f32_e32 v14, v107, v107
	v_mul_f32_e32 v15, v109, v109
	v_fmac_f32_e32 v15, v108, v108
	v_fmac_f32_e32 v15, v110, v110
	v_fmac_f32_e32 v15, v111, v111
	v_add_f32_e32 v38, v12, v13
	v_add_f32_e32 v38, v38, v14
	v_add_f32_e32 v38, v38, v15
	v_pk_mul_f32 v[96:97], v[96:97], v[20:21]
	v_pk_mul_f32 v[98:99], v[98:99], v[22:23]
	v_pk_mul_f32 v[96:97], v[96:97], v[146:147]
	v_pk_mul_f32 v[98:99], v[98:99], v[148:149]
	v_cvt_pk_bf16_f32 v96, v96, v97
	v_cvt_pk_bf16_f32 v97, v98, v99
	v_pk_mul_f32 v[100:101], v[100:101], v[24:25]
	v_pk_mul_f32 v[102:103], v[102:103], v[26:27]
	v_pk_mul_f32 v[100:101], v[100:101], v[150:151]
	v_pk_mul_f32 v[102:103], v[102:103], v[152:153]
	v_cvt_pk_bf16_f32 v100, v100, v101
	v_cvt_pk_bf16_f32 v101, v102, v103
	v_pk_mul_f32 v[104:105], v[104:105], v[28:29]
	v_pk_mul_f32 v[106:107], v[106:107], v[30:31]
	v_pk_mul_f32 v[104:105], v[104:105], v[154:155]
	v_pk_mul_f32 v[106:107], v[106:107], v[156:157]
	v_cvt_pk_bf16_f32 v104, v104, v105
	v_cvt_pk_bf16_f32 v105, v106, v107
	v_pk_mul_f32 v[108:109], v[108:109], v[32:33]
	v_pk_mul_f32 v[110:111], v[110:111], v[34:35]
	v_pk_mul_f32 v[108:109], v[108:109], v[158:159]
	v_pk_mul_f32 v[110:111], v[110:111], v[160:161]
	v_cvt_pk_bf16_f32 v108, v108, v109
	v_cvt_pk_bf16_f32 v109, v110, v111
	global_store_dwordx2 v56, v[96:97], s[14:15]
	global_store_dwordx2 v56, v[100:101], s[14:15] offset:512
	global_store_dwordx2 v56, v[104:105], s[14:15] offset:1024
	global_store_dwordx2 v56, v[108:109], s[14:15] offset:1536
	s_waitcnt vmcnt(20)
	v_mul_f32_e32 v12, v113, v113
	v_fmac_f32_e32 v12, v112, v112
	v_fmac_f32_e32 v12, v114, v114
	v_fmac_f32_e32 v12, v115, v115
	v_mul_f32_e32 v13, v117, v117
	v_fmac_f32_e32 v13, v116, v116
	v_fmac_f32_e32 v13, v118, v118
	v_fmac_f32_e32 v13, v119, v119
	v_mul_f32_e32 v14, v121, v121
	v_fmac_f32_e32 v14, v120, v120
	v_fmac_f32_e32 v14, v122, v122
	v_fmac_f32_e32 v14, v123, v123
	v_mul_f32_e32 v15, v125, v125
	v_fmac_f32_e32 v15, v124, v124
	v_fmac_f32_e32 v15, v126, v126
	v_fmac_f32_e32 v15, v127, v127
	v_add_f32_e32 v39, v12, v13
	v_add_f32_e32 v39, v39, v14
	v_add_f32_e32 v39, v39, v15
	v_pk_mul_f32 v[112:113], v[112:113], v[20:21]
	v_pk_mul_f32 v[114:115], v[114:115], v[22:23]
	v_pk_mul_f32 v[112:113], v[112:113], v[146:147]
	v_pk_mul_f32 v[114:115], v[114:115], v[148:149]
	v_cvt_pk_bf16_f32 v112, v112, v113
	v_cvt_pk_bf16_f32 v113, v114, v115
	v_pk_mul_f32 v[116:117], v[116:117], v[24:25]
	v_pk_mul_f32 v[118:119], v[118:119], v[26:27]
	v_pk_mul_f32 v[116:117], v[116:117], v[150:151]
	v_pk_mul_f32 v[118:119], v[118:119], v[152:153]
	v_cvt_pk_bf16_f32 v116, v116, v117
	v_cvt_pk_bf16_f32 v117, v118, v119
	v_pk_mul_f32 v[120:121], v[120:121], v[28:29]
	v_pk_mul_f32 v[122:123], v[122:123], v[30:31]
	v_pk_mul_f32 v[120:121], v[120:121], v[154:155]
	v_pk_mul_f32 v[122:123], v[122:123], v[156:157]
	v_cvt_pk_bf16_f32 v120, v120, v121
	v_cvt_pk_bf16_f32 v121, v122, v123
	v_pk_mul_f32 v[124:125], v[124:125], v[32:33]
	v_pk_mul_f32 v[126:127], v[126:127], v[34:35]
	v_pk_mul_f32 v[124:125], v[124:125], v[158:159]
	v_pk_mul_f32 v[126:127], v[126:127], v[160:161]
	v_cvt_pk_bf16_f32 v124, v124, v125
	v_cvt_pk_bf16_f32 v125, v126, v127
	global_store_dwordx2 v57, v[112:113], s[14:15]
	global_store_dwordx2 v57, v[116:117], s[14:15] offset:512
	global_store_dwordx2 v57, v[120:121], s[14:15] offset:1024
	global_store_dwordx2 v57, v[124:125], s[14:15] offset:1536
	s_waitcnt vmcnt(20)
	v_mul_f32_e32 v12, v163, v163
	v_fmac_f32_e32 v12, v162, v162
	v_fmac_f32_e32 v12, v164, v164
	v_fmac_f32_e32 v12, v165, v165
	v_mul_f32_e32 v13, v167, v167
	v_fmac_f32_e32 v13, v166, v166
	v_fmac_f32_e32 v13, v168, v168
	v_fmac_f32_e32 v13, v169, v169
	v_mul_f32_e32 v14, v171, v171
	v_fmac_f32_e32 v14, v170, v170
	v_fmac_f32_e32 v14, v172, v172
	v_fmac_f32_e32 v14, v173, v173
	v_mul_f32_e32 v15, v175, v175
	v_fmac_f32_e32 v15, v174, v174
	v_fmac_f32_e32 v15, v176, v176
	v_fmac_f32_e32 v15, v177, v177
	v_add_f32_e32 v40, v12, v13
	v_add_f32_e32 v40, v40, v14
	v_add_f32_e32 v40, v40, v15
	v_pk_mul_f32 v[162:163], v[162:163], v[20:21]
	v_pk_mul_f32 v[164:165], v[164:165], v[22:23]
	v_pk_mul_f32 v[162:163], v[162:163], v[146:147]
	v_pk_mul_f32 v[164:165], v[164:165], v[148:149]
	v_cvt_pk_bf16_f32 v162, v162, v163
	v_cvt_pk_bf16_f32 v163, v164, v165
	v_pk_mul_f32 v[166:167], v[166:167], v[24:25]
	v_pk_mul_f32 v[168:169], v[168:169], v[26:27]
	v_pk_mul_f32 v[166:167], v[166:167], v[150:151]
	v_pk_mul_f32 v[168:169], v[168:169], v[152:153]
	v_cvt_pk_bf16_f32 v166, v166, v167
	v_cvt_pk_bf16_f32 v167, v168, v169
	v_pk_mul_f32 v[170:171], v[170:171], v[28:29]
	v_pk_mul_f32 v[172:173], v[172:173], v[30:31]
	v_pk_mul_f32 v[170:171], v[170:171], v[154:155]
	v_pk_mul_f32 v[172:173], v[172:173], v[156:157]
	v_cvt_pk_bf16_f32 v170, v170, v171
	v_cvt_pk_bf16_f32 v171, v172, v173
	v_pk_mul_f32 v[174:175], v[174:175], v[32:33]
	v_pk_mul_f32 v[176:177], v[176:177], v[34:35]
	v_pk_mul_f32 v[174:175], v[174:175], v[158:159]
	v_pk_mul_f32 v[176:177], v[176:177], v[160:161]
	v_cvt_pk_bf16_f32 v174, v174, v175
	v_cvt_pk_bf16_f32 v175, v176, v177
	global_store_dwordx2 v58, v[162:163], s[14:15]
	global_store_dwordx2 v58, v[166:167], s[14:15] offset:512
	global_store_dwordx2 v58, v[170:171], s[14:15] offset:1024
	global_store_dwordx2 v58, v[174:175], s[14:15] offset:1536
	s_waitcnt vmcnt(20)
	v_mul_f32_e32 v12, v179, v179
	v_fmac_f32_e32 v12, v178, v178
	v_fmac_f32_e32 v12, v180, v180
	v_fmac_f32_e32 v12, v181, v181
	v_mul_f32_e32 v13, v183, v183
	v_fmac_f32_e32 v13, v182, v182
	v_fmac_f32_e32 v13, v184, v184
	v_fmac_f32_e32 v13, v185, v185
	v_mul_f32_e32 v14, v187, v187
	v_fmac_f32_e32 v14, v186, v186
	v_fmac_f32_e32 v14, v188, v188
	v_fmac_f32_e32 v14, v189, v189
	v_mul_f32_e32 v15, v191, v191
	v_fmac_f32_e32 v15, v190, v190
	v_fmac_f32_e32 v15, v192, v192
	v_fmac_f32_e32 v15, v193, v193
	v_add_f32_e32 v41, v12, v13
	v_add_f32_e32 v41, v41, v14
	v_add_f32_e32 v41, v41, v15
	v_pk_mul_f32 v[178:179], v[178:179], v[20:21]
	v_pk_mul_f32 v[180:181], v[180:181], v[22:23]
	v_pk_mul_f32 v[178:179], v[178:179], v[146:147]
	v_pk_mul_f32 v[180:181], v[180:181], v[148:149]
	v_cvt_pk_bf16_f32 v178, v178, v179
	v_cvt_pk_bf16_f32 v179, v180, v181
	v_pk_mul_f32 v[182:183], v[182:183], v[24:25]
	v_pk_mul_f32 v[184:185], v[184:185], v[26:27]
	v_pk_mul_f32 v[182:183], v[182:183], v[150:151]
	v_pk_mul_f32 v[184:185], v[184:185], v[152:153]
	v_cvt_pk_bf16_f32 v182, v182, v183
	v_cvt_pk_bf16_f32 v183, v184, v185
	v_pk_mul_f32 v[186:187], v[186:187], v[28:29]
	v_pk_mul_f32 v[188:189], v[188:189], v[30:31]
	v_pk_mul_f32 v[186:187], v[186:187], v[154:155]
	v_pk_mul_f32 v[188:189], v[188:189], v[156:157]
	v_cvt_pk_bf16_f32 v186, v186, v187
	v_cvt_pk_bf16_f32 v187, v188, v189
	v_pk_mul_f32 v[190:191], v[190:191], v[32:33]
	v_pk_mul_f32 v[192:193], v[192:193], v[34:35]
	v_pk_mul_f32 v[190:191], v[190:191], v[158:159]
	v_pk_mul_f32 v[192:193], v[192:193], v[160:161]
	v_cvt_pk_bf16_f32 v190, v190, v191
	v_cvt_pk_bf16_f32 v191, v192, v193
	global_store_dwordx2 v59, v[178:179], s[14:15]
	global_store_dwordx2 v59, v[182:183], s[14:15] offset:512
	global_store_dwordx2 v59, v[186:187], s[14:15] offset:1024
	global_store_dwordx2 v59, v[190:191], s[14:15] offset:1536
	ds_bpermute_b32 v42, v4, v36
	ds_bpermute_b32 v43, v4, v37
	ds_bpermute_b32 v44, v4, v38
	ds_bpermute_b32 v45, v4, v39
	ds_bpermute_b32 v46, v4, v40
	ds_bpermute_b32 v47, v4, v41
	s_waitcnt lgkmcnt(0)
	v_add_f32_e32 v36, v36, v42
	v_add_f32_e32 v37, v37, v43
	v_add_f32_e32 v38, v38, v44
	v_add_f32_e32 v39, v39, v45
	v_add_f32_e32 v40, v40, v46
	v_add_f32_e32 v41, v41, v47
	ds_bpermute_b32 v42, v5, v36
	ds_bpermute_b32 v43, v5, v37
	ds_bpermute_b32 v44, v5, v38
	ds_bpermute_b32 v45, v5, v39
	ds_bpermute_b32 v46, v5, v40
	ds_bpermute_b32 v47, v5, v41
	s_waitcnt lgkmcnt(0)
	v_add_f32_e32 v36, v36, v42
	v_add_f32_e32 v37, v37, v43
	v_add_f32_e32 v38, v38, v44
	v_add_f32_e32 v39, v39, v45
	v_add_f32_e32 v40, v40, v46
	v_add_f32_e32 v41, v41, v47
	ds_bpermute_b32 v42, v6, v36
	ds_bpermute_b32 v43, v6, v37
	ds_bpermute_b32 v44, v6, v38
	ds_bpermute_b32 v45, v6, v39
	ds_bpermute_b32 v46, v6, v40
	ds_bpermute_b32 v47, v6, v41
	s_waitcnt lgkmcnt(0)
	v_add_f32_e32 v36, v36, v42
	v_add_f32_e32 v37, v37, v43
	v_add_f32_e32 v38, v38, v44
	v_add_f32_e32 v39, v39, v45
	v_add_f32_e32 v40, v40, v46
	v_add_f32_e32 v41, v41, v47
	ds_bpermute_b32 v42, v7, v36
	ds_bpermute_b32 v43, v7, v37
	ds_bpermute_b32 v44, v7, v38
	ds_bpermute_b32 v45, v7, v39
	ds_bpermute_b32 v46, v7, v40
	ds_bpermute_b32 v47, v7, v41
	s_waitcnt lgkmcnt(0)
	v_add_f32_e32 v36, v36, v42
	v_add_f32_e32 v37, v37, v43
	v_add_f32_e32 v38, v38, v44
	v_add_f32_e32 v39, v39, v45
	v_add_f32_e32 v40, v40, v46
	v_add_f32_e32 v41, v41, v47
	ds_bpermute_b32 v42, v8, v36
	ds_bpermute_b32 v43, v8, v37
	ds_bpermute_b32 v44, v8, v38
	ds_bpermute_b32 v45, v8, v39
	ds_bpermute_b32 v46, v8, v40
	ds_bpermute_b32 v47, v8, v41
	s_waitcnt lgkmcnt(0)
	v_add_f32_e32 v36, v36, v42
	v_add_f32_e32 v37, v37, v43
	v_add_f32_e32 v38, v38, v44
	v_add_f32_e32 v39, v39, v45
	v_add_f32_e32 v40, v40, v46
	v_add_f32_e32 v41, v41, v47
	ds_bpermute_b32 v42, v9, v36
	ds_bpermute_b32 v43, v9, v37
	ds_bpermute_b32 v44, v9, v38
	ds_bpermute_b32 v45, v9, v39
	ds_bpermute_b32 v46, v9, v40
	ds_bpermute_b32 v47, v9, v41
	s_waitcnt lgkmcnt(0)
	v_add_f32_e32 v36, v36, v42
	v_add_f32_e32 v37, v37, v43
	v_add_f32_e32 v38, v38, v44
	v_add_f32_e32 v39, v39, v45
	v_add_f32_e32 v40, v40, v46
	v_add_f32_e32 v41, v41, v47
	s_and_saveexec_b64 s[2:3], s[36:37]
	v_cndmask_b32_e64 v36, 0, v36, s[38:39]
	v_cndmask_b32_e64 v37, 0, v37, s[38:39]
	v_cndmask_b32_e64 v38, 0, v38, s[38:39]
	v_cndmask_b32_e64 v39, 0, v39, s[38:39]
	v_cndmask_b32_e64 v40, 0, v40, s[38:39]
	v_cndmask_b32_e64 v41, 0, v41, s[38:39]
	global_store_dword v60, v36, s[16:17]
	global_store_dword v61, v37, s[16:17]
	global_store_dword v62, v38, s[16:17]
	global_store_dword v63, v39, s[16:17]
	global_store_dword v16, v40, s[16:17]
	global_store_dword v17, v41, s[16:17]
	s_or_b64 exec, exec, s[2:3]
.Lxg6_end:
	v_readlane_b32 s40, v254, 57
	v_readlane_b32 s41, v254, 58
	v_readlane_b32 s42, v254, 59
	v_readlane_b32 s43, v254, 60
	v_readlane_b32 s44, v254, 61
	v_readlane_b32 s45, v254, 62
	v_readlane_b32 s46, v254, 63
	v_readlane_b32 s47, v255, 0
	v_readlane_b32 s48, v255, 1
	v_readlane_b32 s49, v255, 2
	v_readlane_b32 s50, v255, 3
	v_readlane_b32 s51, v255, 4
	v_readlane_b32 s52, v255, 5
	v_readlane_b32 s53, v255, 6
	v_readlane_b32 s54, v255, 7
	v_readlane_b32 s55, v255, 8
	v_mov_b32_e32 v10, 0
	s_branch .LBB0_94
